# phase 1: Pcat trips split between each table wave (trips 0-1) and the row wave of the same index (trips 2-3)
# baseline (speedup 1.0000x reference)
.LBB0_121:
	s_nop 1
	v_or_b32_e32 v6, s3, v64
	s_mov_b32 s0, 0x300000
	v_cmp_gt_i32_e32 vcc, s0, v6
	s_and_saveexec_b64 s[0:1], vcc
	v_readlane_b32 s94, v248, 1
	v_readlane_b32 s95, v248, 2
	s_mov_b32 s98, 0x80000
	s_cbranch_execz .LBB0_164

.Lmcat_done:
	s_cmp_gt_i32 s38, 3
	s_mov_b32 s98, 0x80000
	s_cbranch_scc1 .LBB0_164
	s_lshl_b32 s99, s6, 2
	s_add_i32 s99, s99, s38
	s_lshl_b32 s99, s99, 6
	v_and_b32_e32 v6, 63, v193
	v_or_b32_e32 v6, s99, v6
	v_add_u32_e32 v6, 0x80000, v6
	s_mov_b32 s98, 0x100000
	s_mov_b64 s[0:1], exec
	s_branch .LBB0_164

.LBB0_164:
	s_or_b64 exec, exec, s[0:1]
	s_mov_b32 s0, s98
	v_cmp_gt_i32_e32 vcc, s0, v6
	s_and_saveexec_b64 s[8:9], vcc
	s_cbranch_execz .LBB0_167
	s_add_u32 s10, s90, 0x3760000
	s_addc_u32 s11, s91, 0
	s_add_u32 s12, s90, 0x3fe0000
	s_addc_u32 s13, s91, 0
	s_add_u32 s14, s90, 0x40e8000
	s_addc_u32 s15, s91, 0
	s_lshl_b32 s2, s92, 9
	s_mul_i32 s3, s92, 0x300
	v_lshlrev_b32_e32 v2, 2, v6
	s_lshl_b32 s7, s92, 12
	s_mov_b64 s[16:17], 0
	v_mov_b32_e32 v1, 0
	s_add_i32 s18, s98, -1
